# UV PEER sweep: lists ordered token-major inside each 4-partition chunk (fewer padded batches), no per-partition build loop
# speedup vs baseline: 1.0593x; 1.0445x over previous
; __device__ __forceinline__ void peer_tile(const Args& A, LAS unsigned char* lds, int tile) {
;     ...
;     for (int ti = 0; ti < 8; ++ti) {
;         const int tl = 8 * w + ti;
;         const u32x2 e0 = SEL[tl * 128 + lane], e1 = SEL[tl * 128 + 64 + lane];
;         const int p0 = (int)(e0.x >> 10), p1 = (int)(e1.x >> 10);
;         int off = 0;
;         for (int p = 0; p < 16; ++p) {
;             const unsigned long long m0 = __ballot(p0 == p), m1 = __ballot(p1 == p);
;             const int c0 = __popcll(m0), c1 = __popcll(m1);
;             const int r0 = __builtin_amdgcn_mbcnt_hi((unsigned)(m0 >> 32), __builtin_amdgcn_mbcnt_lo((unsigned)m0, 0u));
;             const int r1 = __builtin_amdgcn_mbcnt_hi((unsigned)(m1 >> 32), __builtin_amdgcn_mbcnt_lo((unsigned)m1, 0u));
;             if (p0 == p) SORT[tl * 128 + off + r0] = e0;
;             if (p1 == p) SORT[tl * 128 + off + c0 + r1] = e1;
;             if (lane == 0) OFFS[tl * 17 + p] = off;
;             off += c0 + c1;
;         }
;         if (lane == 0) OFFS[tl * 17 + 16] = off;
;     }
.LU_win:
	v_mov_b32_e32 v216, 0
	v_mov_b32_e32 v217, 0
	v_mov_b32_e32 v218, 0x11fe80
	v_mov_b32_e32 v219, 0
	v_add_u32_e32 v220, s22, v240
	ds_write_b128 v220, v[216:219] offset:0
	ds_write_b128 v220, v[216:219] offset:1024
	ds_write_b128 v220, v[216:219] offset:2048
	ds_write_b128 v220, v[216:219] offset:3072
	ds_write_b128 v220, v[216:219] offset:4096
	ds_write_b128 v220, v[216:219] offset:5120
	ds_write_b128 v220, v[216:219] offset:6144
	ds_write_b128 v220, v[216:219] offset:7168
	s_mov_b32 exec_hi, 0
	ds_write_b128 v220, v[216:219] offset:8192
	s_mov_b64 exec, -1
	s_lshl_b32 s0, s76, 10
	s_add_i32 s0, s0, 0x11000
	v_lshrrev_b32_e32 v221, 1, v240
	v_add_u32_e32 v221, s0, v221
	ds_read_b64 v[128:129], v221 offset:0
	ds_read_b64 v[132:133], v221 offset:512
	ds_read_b64 v[136:137], v221 offset:1024
	ds_read_b64 v[140:141], v221 offset:1536
	ds_read_b64 v[144:145], v221 offset:2048
	ds_read_b64 v[148:149], v221 offset:2560
	ds_read_b64 v[152:153], v221 offset:3072
	ds_read_b64 v[156:157], v221 offset:3584
	ds_read_b64 v[160:161], v221 offset:4096
	ds_read_b64 v[164:165], v221 offset:4608
	ds_read_b64 v[168:169], v221 offset:5120
	ds_read_b64 v[172:173], v221 offset:5632
	ds_read_b64 v[176:177], v221 offset:6144
	ds_read_b64 v[180:181], v221 offset:6656
	ds_read_b64 v[184:185], v221 offset:7168
	ds_read_b64 v[188:189], v221 offset:7680
	s_waitcnt lgkmcnt(0)
	v_lshrrev_b32_e32 v192, 12, v128
	v_lshlrev_b32_e32 v128, 10, v128
	v_add_u32_e32 v130, 4, v221
	v_lshl_or_b32 v130, v130, 3, 0
	v_mov_b32_e32 v131, 0
	v_lshrrev_b32_e32 v193, 12, v132
	v_lshlrev_b32_e32 v132, 10, v132
	v_add_u32_e32 v134, 516, v221
	v_lshl_or_b32 v134, v134, 3, 0
	v_mov_b32_e32 v135, 0
	v_lshrrev_b32_e32 v194, 12, v136
	v_lshlrev_b32_e32 v136, 10, v136
	v_add_u32_e32 v138, 1028, v221
	v_lshl_or_b32 v138, v138, 3, 1
	v_mov_b32_e32 v139, 0
	v_lshrrev_b32_e32 v195, 12, v140
	v_lshlrev_b32_e32 v140, 10, v140
	v_add_u32_e32 v142, 1540, v221
	v_lshl_or_b32 v142, v142, 3, 1
	v_mov_b32_e32 v143, 0
	v_lshrrev_b32_e32 v196, 12, v144
	v_lshlrev_b32_e32 v144, 10, v144
	v_add_u32_e32 v146, 2052, v221
	v_lshl_or_b32 v146, v146, 3, 2
	v_mov_b32_e32 v147, 0
	v_lshrrev_b32_e32 v197, 12, v148
	v_lshlrev_b32_e32 v148, 10, v148
	v_add_u32_e32 v150, 2564, v221
	v_lshl_or_b32 v150, v150, 3, 2
	v_mov_b32_e32 v151, 0
	v_lshrrev_b32_e32 v198, 12, v152
	v_lshlrev_b32_e32 v152, 10, v152
	v_add_u32_e32 v154, 3076, v221
	v_lshl_or_b32 v154, v154, 3, 3
	v_mov_b32_e32 v155, 0
	v_lshrrev_b32_e32 v199, 12, v156
	v_lshlrev_b32_e32 v156, 10, v156
	v_add_u32_e32 v158, 3588, v221
	v_lshl_or_b32 v158, v158, 3, 3
	v_mov_b32_e32 v159, 0
	v_lshrrev_b32_e32 v200, 12, v160
	v_lshlrev_b32_e32 v160, 10, v160
	v_add_u32_e32 v162, 4100, v221
	v_lshl_or_b32 v162, v162, 3, 4
	v_mov_b32_e32 v163, 0
	v_lshrrev_b32_e32 v201, 12, v164
	v_lshlrev_b32_e32 v164, 10, v164
	v_add_u32_e32 v166, 4612, v221
	v_lshl_or_b32 v166, v166, 3, 4
	v_mov_b32_e32 v167, 0
	v_lshrrev_b32_e32 v202, 12, v168
	v_lshlrev_b32_e32 v168, 10, v168
	v_add_u32_e32 v170, 5124, v221
	v_lshl_or_b32 v170, v170, 3, 5
	v_mov_b32_e32 v171, 0
	v_lshrrev_b32_e32 v203, 12, v172
	v_lshlrev_b32_e32 v172, 10, v172
	v_add_u32_e32 v174, 5636, v221
	v_lshl_or_b32 v174, v174, 3, 5
	v_mov_b32_e32 v175, 0
	v_lshrrev_b32_e32 v204, 12, v176
	v_lshlrev_b32_e32 v176, 10, v176
	v_add_u32_e32 v178, 6148, v221
	v_lshl_or_b32 v178, v178, 3, 6
	v_mov_b32_e32 v179, 0
	v_lshrrev_b32_e32 v205, 12, v180
	v_lshlrev_b32_e32 v180, 10, v180
	v_add_u32_e32 v182, 6660, v221
	v_lshl_or_b32 v182, v182, 3, 6
	v_mov_b32_e32 v183, 0
	v_lshrrev_b32_e32 v206, 12, v184
	v_lshlrev_b32_e32 v184, 10, v184
	v_add_u32_e32 v186, 7172, v221
	v_lshl_or_b32 v186, v186, 3, 7
	v_mov_b32_e32 v187, 0
	v_lshrrev_b32_e32 v207, 12, v188
	v_lshlrev_b32_e32 v188, 10, v188
	v_add_u32_e32 v190, 7684, v221
	v_lshl_or_b32 v190, v190, 3, 7
	v_mov_b32_e32 v191, 0
	s_mov_b32 s74, s89
	s_mov_b32 s75, 0
	s_lshl_b32 s37, s90, 2
	s_mov_b32 s42, 512
.LU_bp:
	v_cmp_eq_u32_e64 s[68:69], s74, v192
	v_cmp_eq_u32_e64 s[70:71], s74, v193
	s_nop 0
	s_lshl_b32 s3, s75, 2
	s_sub_i32 s3, s3, s37
	s_bcnt1_i32_b64 s0, s[68:69]
	s_bcnt1_i32_b64 s1, s[70:71]
	v_mbcnt_lo_u32_b32 v222, s68, 0
	v_mbcnt_hi_u32_b32 v222, s69, v222
	v_mbcnt_lo_u32_b32 v223, s70, 0
	v_mbcnt_hi_u32_b32 v223, s71, v223
	v_add_u32_e32 v222, s3, v222
	v_add_u32_e32 v223, s0, v223
	v_add_u32_e32 v223, s3, v223
	v_cmp_gt_u32_e64 s[38:39], s42, v222
	v_cmp_gt_u32_e64 s[40:41], s42, v223
	v_lshl_add_u32 v222, v222, 4, s22
	v_lshl_add_u32 v223, v223, 4, s22
	s_and_b64 exec, s[68:69], s[38:39]
	ds_write_b128 v222, v[128:131]
	s_and_b64 exec, s[70:71], s[40:41]
	ds_write_b128 v223, v[132:135]
	s_mov_b64 exec, -1
	s_add_i32 s0, s0, s1
	s_add_i32 s0, s0, 3
	s_lshr_b32 s0, s0, 2
	s_add_i32 s75, s75, s0
	v_cmp_eq_u32_e64 s[68:69], s74, v194
	v_cmp_eq_u32_e64 s[70:71], s74, v195
	s_nop 0
	s_lshl_b32 s3, s75, 2
	s_sub_i32 s3, s3, s37
	s_bcnt1_i32_b64 s0, s[68:69]
	s_bcnt1_i32_b64 s1, s[70:71]
	v_mbcnt_lo_u32_b32 v222, s68, 0
	v_mbcnt_hi_u32_b32 v222, s69, v222
	v_mbcnt_lo_u32_b32 v223, s70, 0
	v_mbcnt_hi_u32_b32 v223, s71, v223
	v_add_u32_e32 v222, s3, v222
	v_add_u32_e32 v223, s0, v223
	v_add_u32_e32 v223, s3, v223
	v_cmp_gt_u32_e64 s[38:39], s42, v222
	v_cmp_gt_u32_e64 s[40:41], s42, v223
	v_lshl_add_u32 v222, v222, 4, s22
	v_lshl_add_u32 v223, v223, 4, s22
	s_and_b64 exec, s[68:69], s[38:39]
	ds_write_b128 v222, v[136:139]
	s_and_b64 exec, s[70:71], s[40:41]
	ds_write_b128 v223, v[140:143]
	s_mov_b64 exec, -1
	s_add_i32 s0, s0, s1
	s_add_i32 s0, s0, 3
	s_lshr_b32 s0, s0, 2
	s_add_i32 s75, s75, s0
	v_cmp_eq_u32_e64 s[68:69], s74, v196
	v_cmp_eq_u32_e64 s[70:71], s74, v197
; __device__ __forceinline__ void peer_tile(const Args& A, LAS unsigned char* lds, int tile) {
;     ...
;     for (int ti = 0; ti < 8; ++ti) {
;         const int tl = 8 * w + ti;
;         const u32x2 e0 = SEL[tl * 128 + lane], e1 = SEL[tl * 128 + 64 + lane];
;         const int p0 = (int)(e0.x >> 10), p1 = (int)(e1.x >> 10);
;         int off = 0;
;         for (int p = 0; p < 16; ++p) {
;             const unsigned long long m0 = __ballot(p0 == p), m1 = __ballot(p1 == p);
;             const int c0 = __popcll(m0), c1 = __popcll(m1);
;             const int r0 = __builtin_amdgcn_mbcnt_hi((unsigned)(m0 >> 32), __builtin_amdgcn_mbcnt_lo((unsigned)m0, 0u));
;             const int r1 = __builtin_amdgcn_mbcnt_hi((unsigned)(m1 >> 32), __builtin_amdgcn_mbcnt_lo((unsigned)m1, 0u));
;             if (p0 == p) SORT[tl * 128 + off + r0] = e0;
;             if (p1 == p) SORT[tl * 128 + off + c0 + r1] = e1;
;             if (lane == 0) OFFS[tl * 17 + p] = off;
;             off += c0 + c1;
;         }
;         if (lane == 0) OFFS[tl * 17 + 16] = off;
;     }
	s_nop 0
	s_lshl_b32 s3, s75, 2
	s_sub_i32 s3, s3, s37
	s_bcnt1_i32_b64 s0, s[68:69]
	s_bcnt1_i32_b64 s1, s[70:71]
	v_mbcnt_lo_u32_b32 v222, s68, 0
	v_mbcnt_hi_u32_b32 v222, s69, v222
	v_mbcnt_lo_u32_b32 v223, s70, 0
	v_mbcnt_hi_u32_b32 v223, s71, v223
	v_add_u32_e32 v222, s3, v222
	v_add_u32_e32 v223, s0, v223
	v_add_u32_e32 v223, s3, v223
	v_cmp_gt_u32_e64 s[38:39], s42, v222
	v_cmp_gt_u32_e64 s[40:41], s42, v223
	v_lshl_add_u32 v222, v222, 4, s22
	v_lshl_add_u32 v223, v223, 4, s22
	s_and_b64 exec, s[68:69], s[38:39]
	ds_write_b128 v222, v[144:147]
	s_and_b64 exec, s[70:71], s[40:41]
	ds_write_b128 v223, v[148:151]
	s_mov_b64 exec, -1
	s_add_i32 s0, s0, s1
	s_add_i32 s0, s0, 3
	s_lshr_b32 s0, s0, 2
	s_add_i32 s75, s75, s0
	v_cmp_eq_u32_e64 s[68:69], s74, v198
	v_cmp_eq_u32_e64 s[70:71], s74, v199
	s_nop 0
	s_lshl_b32 s3, s75, 2
	s_sub_i32 s3, s3, s37
	s_bcnt1_i32_b64 s0, s[68:69]
	s_bcnt1_i32_b64 s1, s[70:71]
	v_mbcnt_lo_u32_b32 v222, s68, 0
	v_mbcnt_hi_u32_b32 v222, s69, v222
	v_mbcnt_lo_u32_b32 v223, s70, 0
	v_mbcnt_hi_u32_b32 v223, s71, v223
	v_add_u32_e32 v222, s3, v222
	v_add_u32_e32 v223, s0, v223
	v_add_u32_e32 v223, s3, v223
	v_cmp_gt_u32_e64 s[38:39], s42, v222
	v_cmp_gt_u32_e64 s[40:41], s42, v223
	v_lshl_add_u32 v222, v222, 4, s22
	v_lshl_add_u32 v223, v223, 4, s22
	s_and_b64 exec, s[68:69], s[38:39]
	ds_write_b128 v222, v[152:155]
	s_and_b64 exec, s[70:71], s[40:41]
	ds_write_b128 v223, v[156:159]
	s_mov_b64 exec, -1
	s_add_i32 s0, s0, s1
	s_add_i32 s0, s0, 3
	s_lshr_b32 s0, s0, 2
	s_add_i32 s75, s75, s0
	v_cmp_eq_u32_e64 s[68:69], s74, v200
	v_cmp_eq_u32_e64 s[70:71], s74, v201
	s_nop 0
	s_lshl_b32 s3, s75, 2
	s_sub_i32 s3, s3, s37
	s_bcnt1_i32_b64 s0, s[68:69]
	s_bcnt1_i32_b64 s1, s[70:71]
	v_mbcnt_lo_u32_b32 v222, s68, 0
	v_mbcnt_hi_u32_b32 v222, s69, v222
	v_mbcnt_lo_u32_b32 v223, s70, 0
	v_mbcnt_hi_u32_b32 v223, s71, v223
	v_add_u32_e32 v222, s3, v222
	v_add_u32_e32 v223, s0, v223
	v_add_u32_e32 v223, s3, v223
	v_cmp_gt_u32_e64 s[38:39], s42, v222
	v_cmp_gt_u32_e64 s[40:41], s42, v223
	v_lshl_add_u32 v222, v222, 4, s22
	v_lshl_add_u32 v223, v223, 4, s22
	s_and_b64 exec, s[68:69], s[38:39]
	ds_write_b128 v222, v[160:163]
	s_and_b64 exec, s[70:71], s[40:41]
	ds_write_b128 v223, v[164:167]
	s_mov_b64 exec, -1
	s_add_i32 s0, s0, s1
	s_add_i32 s0, s0, 3
	s_lshr_b32 s0, s0, 2
	s_add_i32 s75, s75, s0
	v_cmp_eq_u32_e64 s[68:69], s74, v202
	v_cmp_eq_u32_e64 s[70:71], s74, v203
	s_nop 0
	s_lshl_b32 s3, s75, 2
	s_sub_i32 s3, s3, s37
	s_bcnt1_i32_b64 s0, s[68:69]
	s_bcnt1_i32_b64 s1, s[70:71]
	v_mbcnt_lo_u32_b32 v222, s68, 0
	v_mbcnt_hi_u32_b32 v222, s69, v222
	v_mbcnt_lo_u32_b32 v223, s70, 0
	v_mbcnt_hi_u32_b32 v223, s71, v223
	v_add_u32_e32 v222, s3, v222
	v_add_u32_e32 v223, s0, v223
	v_add_u32_e32 v223, s3, v223
	v_cmp_gt_u32_e64 s[38:39], s42, v222
	v_cmp_gt_u32_e64 s[40:41], s42, v223
	v_lshl_add_u32 v222, v222, 4, s22
	v_lshl_add_u32 v223, v223, 4, s22
	s_and_b64 exec, s[68:69], s[38:39]
	ds_write_b128 v222, v[168:171]
	s_and_b64 exec, s[70:71], s[40:41]
	ds_write_b128 v223, v[172:175]
	s_mov_b64 exec, -1
	s_add_i32 s0, s0, s1
	s_add_i32 s0, s0, 3
	s_lshr_b32 s0, s0, 2
	s_add_i32 s75, s75, s0
	v_cmp_eq_u32_e64 s[68:69], s74, v204
	v_cmp_eq_u32_e64 s[70:71], s74, v205
	s_nop 0
	s_lshl_b32 s3, s75, 2
	s_sub_i32 s3, s3, s37
	s_bcnt1_i32_b64 s0, s[68:69]
	s_bcnt1_i32_b64 s1, s[70:71]
	v_mbcnt_lo_u32_b32 v222, s68, 0
	v_mbcnt_hi_u32_b32 v222, s69, v222
	v_mbcnt_lo_u32_b32 v223, s70, 0
	v_mbcnt_hi_u32_b32 v223, s71, v223
	v_add_u32_e32 v222, s3, v222
	v_add_u32_e32 v223, s0, v223
	v_add_u32_e32 v223, s3, v223
	v_cmp_gt_u32_e64 s[38:39], s42, v222
	v_cmp_gt_u32_e64 s[40:41], s42, v223
	v_lshl_add_u32 v222, v222, 4, s22
	v_lshl_add_u32 v223, v223, 4, s22
	s_and_b64 exec, s[68:69], s[38:39]
	ds_write_b128 v222, v[176:179]
	s_and_b64 exec, s[70:71], s[40:41]
	ds_write_b128 v223, v[180:183]
	s_mov_b64 exec, -1
	s_add_i32 s0, s0, s1
	s_add_i32 s0, s0, 3
	s_lshr_b32 s0, s0, 2
	s_add_i32 s75, s75, s0
	v_cmp_eq_u32_e64 s[68:69], s74, v206
	v_cmp_eq_u32_e64 s[70:71], s74, v207
	s_nop 0
	s_lshl_b32 s3, s75, 2
	s_sub_i32 s3, s3, s37
	s_bcnt1_i32_b64 s0, s[68:69]
	s_bcnt1_i32_b64 s1, s[70:71]
	v_mbcnt_lo_u32_b32 v222, s68, 0
	v_mbcnt_hi_u32_b32 v222, s69, v222
	v_mbcnt_lo_u32_b32 v223, s70, 0
	v_mbcnt_hi_u32_b32 v223, s71, v223
	v_add_u32_e32 v222, s3, v222
	v_add_u32_e32 v223, s0, v223
	v_add_u32_e32 v223, s3, v223
	v_cmp_gt_u32_e64 s[38:39], s42, v222
	v_cmp_gt_u32_e64 s[40:41], s42, v223
	v_lshl_add_u32 v222, v222, 4, s22
	v_lshl_add_u32 v223, v223, 4, s22
	s_and_b64 exec, s[68:69], s[38:39]
	ds_write_b128 v222, v[184:187]
	s_and_b64 exec, s[70:71], s[40:41]
	ds_write_b128 v223, v[188:191]
	s_mov_b64 exec, -1
	s_add_i32 s0, s0, s1
	s_add_i32 s0, s0, 3
	s_lshr_b32 s0, s0, 2
	s_add_i32 s75, s75, s0
	s_mov_b32 s91, s75
	s_sub_i32 s20, s91, s90
	s_min_u32 s20, s20, 128
	s_waitcnt vmcnt(0) lgkmcnt(0)
	v_add_u32_e32 v241, s22, v247
	ds_read_b128 v[232:235], v241 offset:0
	s_waitcnt lgkmcnt(0)
	v_readlane_b32 s64, v232, 0
	v_readlane_b32 s65, v232, 16
	v_readlane_b32 s66, v232, 32
	v_readlane_b32 s67, v232, 48
	v_lshrrev_b32_e32 v253, 8, v232
	s_add_u32 s24, s4, s64
	s_addc_u32 s25, s5, 0
	s_add_u32 s26, s4, s65
	s_addc_u32 s27, s5, 0
	s_add_u32 s28, s4, s66
	s_addc_u32 s29, s5, 0
	s_add_u32 s30, s4, s67
	s_addc_u32 s31, s5, 0
	global_load_dwordx4 v[128:131], v240, s[24:25]
	global_load_dwordx4 v[132:135], v240, s[26:27]
	global_load_dwordx4 v[136:139], v240, s[28:29]
	global_load_dwordx4 v[140:143], v240, s[30:31]
	global_load_dword v248, v253, s[8:9]
	global_load_dword v208, v253, s[52:53]
	ds_read_b128 v[232:235], v241 offset:64
	s_waitcnt lgkmcnt(0)
	v_readlane_b32 s64, v232, 0
	v_readlane_b32 s65, v232, 16
	v_readlane_b32 s66, v232, 32
	v_readlane_b32 s67, v232, 48
	v_lshrrev_b32_e32 v253, 8, v232
	s_add_u32 s24, s4, s64
	s_addc_u32 s25, s5, 0
	s_add_u32 s26, s4, s65
	s_addc_u32 s27, s5, 0
	s_add_u32 s28, s4, s66
	s_addc_u32 s29, s5, 0
	s_add_u32 s30, s4, s67
	s_addc_u32 s31, s5, 0
	global_load_dwordx4 v[144:147], v240, s[24:25]
	global_load_dwordx4 v[148:151], v240, s[26:27]
	global_load_dwordx4 v[152:155], v240, s[28:29]
	global_load_dwordx4 v[156:159], v240, s[30:31]
	global_load_dword v249, v253, s[8:9]
	global_load_dword v209, v253, s[52:53]
	ds_read_b128 v[232:235], v241 offset:128
	s_waitcnt lgkmcnt(0)
	v_readlane_b32 s64, v232, 0
	v_readlane_b32 s65, v232, 16
	v_readlane_b32 s66, v232, 32
	v_readlane_b32 s67, v232, 48
	v_lshrrev_b32_e32 v253, 8, v232
	s_add_u32 s24, s4, s64
	s_addc_u32 s25, s5, 0
	s_add_u32 s26, s4, s65
	s_addc_u32 s27, s5, 0
	s_add_u32 s28, s4, s66
	s_addc_u32 s29, s5, 0
	s_add_u32 s30, s4, s67
	s_addc_u32 s31, s5, 0
	global_load_dwordx4 v[160:163], v240, s[24:25]
	global_load_dwordx4 v[164:167], v240, s[26:27]
	global_load_dwordx4 v[168:171], v240, s[28:29]
	global_load_dwordx4 v[172:175], v240, s[30:31]
	global_load_dword v250, v253, s[8:9]
	global_load_dword v210, v253, s[52:53]
	ds_read_b128 v[232:235], v241 offset:192
	s_waitcnt lgkmcnt(0)
	v_readlane_b32 s64, v232, 0
	v_readlane_b32 s65, v232, 16
	v_readlane_b32 s66, v232, 32
	v_readlane_b32 s67, v232, 48
	v_lshrrev_b32_e32 v253, 8, v232
	s_add_u32 s24, s4, s64
	s_addc_u32 s25, s5, 0
	s_add_u32 s26, s4, s65
	s_addc_u32 s27, s5, 0
	s_add_u32 s28, s4, s66
	s_addc_u32 s29, s5, 0
	s_add_u32 s30, s4, s67
	s_addc_u32 s31, s5, 0
	global_load_dwordx4 v[176:179], v240, s[24:25]
	global_load_dwordx4 v[180:183], v240, s[26:27]
	global_load_dwordx4 v[184:187], v240, s[28:29]
	global_load_dwordx4 v[188:191], v240, s[30:31]
	global_load_dword v251, v253, s[8:9]
	global_load_dword v211, v253, s[52:53]
	ds_read_b128 v[236:239], v241 offset:0
	ds_read_b128 v[232:235], v241 offset:256
	s_mov_b32 s21, 0

; __device__ __forceinline__ void peer_tile(const Args& A, LAS unsigned char* lds, int tile) {
;     ...
;     for (int ti = 0; ti < 8; ++ti) {
;         const int tl = 8 * w + ti;
;         const u32x2 e0 = SEL[tl * 128 + lane], e1 = SEL[tl * 128 + 64 + lane];
;         const int p0 = (int)(e0.x >> 10), p1 = (int)(e1.x >> 10);
;         int off = 0;
;         for (int p = 0; p < 16; ++p) {
;             const unsigned long long m0 = __ballot(p0 == p), m1 = __ballot(p1 == p);
;             const int c0 = __popcll(m0), c1 = __popcll(m1);
;             const int r0 = __builtin_amdgcn_mbcnt_hi((unsigned)(m0 >> 32), __builtin_amdgcn_mbcnt_lo((unsigned)m0, 0u));
;             const int r1 = __builtin_amdgcn_mbcnt_hi((unsigned)(m1 >> 32), __builtin_amdgcn_mbcnt_lo((unsigned)m1, 0u));
;             if (p0 == p) SORT[tl * 128 + off + r0] = e0;
;             if (p1 == p) SORT[tl * 128 + off + c0 + r1] = e1;
;             if (lane == 0) OFFS[tl * 17 + p] = off;
;             off += c0 + c1;
;         }
;         if (lane == 0) OFFS[tl * 17 + 16] = off;
;     }
.LV_win:
	v_mov_b32_e32 v216, 0
	v_mov_b32_e32 v217, 0
	v_mov_b32_e32 v218, 0x0
	v_mov_b32_e32 v219, 0
	v_add_u32_e32 v220, s22, v240
	ds_write_b128 v220, v[216:219] offset:0
	ds_write_b128 v220, v[216:219] offset:1024
	ds_write_b128 v220, v[216:219] offset:2048
	ds_write_b128 v220, v[216:219] offset:3072
	ds_write_b128 v220, v[216:219] offset:4096
	ds_write_b128 v220, v[216:219] offset:5120
	ds_write_b128 v220, v[216:219] offset:6144
	ds_write_b128 v220, v[216:219] offset:7168
	s_mov_b32 exec_hi, 0
	ds_write_b128 v220, v[216:219] offset:8192
	s_mov_b64 exec, -1
	s_lshl_b32 s0, s76, 10
	s_add_i32 s0, s0, 0x11000
	v_lshrrev_b32_e32 v221, 1, v240
	v_add_u32_e32 v221, s0, v221
	ds_read_b64 v[128:129], v221 offset:0
	ds_read_b64 v[132:133], v221 offset:512
	ds_read_b64 v[136:137], v221 offset:1024
	ds_read_b64 v[140:141], v221 offset:1536
	ds_read_b64 v[144:145], v221 offset:2048
	ds_read_b64 v[148:149], v221 offset:2560
	ds_read_b64 v[152:153], v221 offset:3072
	ds_read_b64 v[156:157], v221 offset:3584
	ds_read_b64 v[160:161], v221 offset:4096
	ds_read_b64 v[164:165], v221 offset:4608
	ds_read_b64 v[168:169], v221 offset:5120
	ds_read_b64 v[172:173], v221 offset:5632
	ds_read_b64 v[176:177], v221 offset:6144
	ds_read_b64 v[180:181], v221 offset:6656
	ds_read_b64 v[184:185], v221 offset:7168
	ds_read_b64 v[188:189], v221 offset:7680
	s_waitcnt lgkmcnt(0)
	v_lshrrev_b32_e32 v192, 12, v128
	v_lshlrev_b32_e32 v128, 10, v128
	v_mov_b32_e32 v130, 0
	v_mov_b32_e32 v131, 0
	v_lshrrev_b32_e32 v193, 12, v132
	v_lshlrev_b32_e32 v132, 10, v132
	v_mov_b32_e32 v134, 0
	v_mov_b32_e32 v135, 0
	v_lshrrev_b32_e32 v194, 12, v136
	v_lshlrev_b32_e32 v136, 10, v136
	v_mov_b32_e32 v138, 1
	v_mov_b32_e32 v139, 0
	v_lshrrev_b32_e32 v195, 12, v140
	v_lshlrev_b32_e32 v140, 10, v140
	v_mov_b32_e32 v142, 1
	v_mov_b32_e32 v143, 0
	v_lshrrev_b32_e32 v196, 12, v144
	v_lshlrev_b32_e32 v144, 10, v144
	v_mov_b32_e32 v146, 2
	v_mov_b32_e32 v147, 0
	v_lshrrev_b32_e32 v197, 12, v148
	v_lshlrev_b32_e32 v148, 10, v148
	v_mov_b32_e32 v150, 2
	v_mov_b32_e32 v151, 0
	v_lshrrev_b32_e32 v198, 12, v152
	v_lshlrev_b32_e32 v152, 10, v152
	v_mov_b32_e32 v154, 3
	v_mov_b32_e32 v155, 0
	v_lshrrev_b32_e32 v199, 12, v156
	v_lshlrev_b32_e32 v156, 10, v156
	v_mov_b32_e32 v158, 3
	v_mov_b32_e32 v159, 0
	v_lshrrev_b32_e32 v200, 12, v160
	v_lshlrev_b32_e32 v160, 10, v160
	v_mov_b32_e32 v162, 4
	v_mov_b32_e32 v163, 0
	v_lshrrev_b32_e32 v201, 12, v164
	v_lshlrev_b32_e32 v164, 10, v164
	v_mov_b32_e32 v166, 4
	v_mov_b32_e32 v167, 0
	v_lshrrev_b32_e32 v202, 12, v168
	v_lshlrev_b32_e32 v168, 10, v168
	v_mov_b32_e32 v170, 5
	v_mov_b32_e32 v171, 0
	v_lshrrev_b32_e32 v203, 12, v172
	v_lshlrev_b32_e32 v172, 10, v172
	v_mov_b32_e32 v174, 5
	v_mov_b32_e32 v175, 0
	v_lshrrev_b32_e32 v204, 12, v176
	v_lshlrev_b32_e32 v176, 10, v176
	v_mov_b32_e32 v178, 6
	v_mov_b32_e32 v179, 0
	v_lshrrev_b32_e32 v205, 12, v180
	v_lshlrev_b32_e32 v180, 10, v180
	v_mov_b32_e32 v182, 6
	v_mov_b32_e32 v183, 0
	v_lshrrev_b32_e32 v206, 12, v184
	v_lshlrev_b32_e32 v184, 10, v184
	v_mov_b32_e32 v186, 7
	v_mov_b32_e32 v187, 0
	v_lshrrev_b32_e32 v207, 12, v188
	v_lshlrev_b32_e32 v188, 10, v188
	v_mov_b32_e32 v190, 7
	v_mov_b32_e32 v191, 0
	s_mov_b32 s74, s89
	s_mov_b32 s75, 0
	s_lshl_b32 s37, s90, 2
	s_mov_b32 s42, 512
.LV_bp:
	v_cmp_eq_u32_e64 s[68:69], s74, v192
	v_cmp_eq_u32_e64 s[70:71], s74, v193
	s_nop 0
	s_lshl_b32 s3, s75, 2
	s_sub_i32 s3, s3, s37
	s_bcnt1_i32_b64 s0, s[68:69]
	s_bcnt1_i32_b64 s1, s[70:71]
	v_mbcnt_lo_u32_b32 v222, s68, 0
	v_mbcnt_hi_u32_b32 v222, s69, v222
	v_mbcnt_lo_u32_b32 v223, s70, 0
	v_mbcnt_hi_u32_b32 v223, s71, v223
	v_add_u32_e32 v222, s3, v222
	v_add_u32_e32 v223, s0, v223
	v_add_u32_e32 v223, s3, v223
	v_cmp_gt_u32_e64 s[38:39], s42, v222
	v_cmp_gt_u32_e64 s[40:41], s42, v223
	v_lshl_add_u32 v222, v222, 4, s22
	v_lshl_add_u32 v223, v223, 4, s22
	s_and_b64 exec, s[68:69], s[38:39]
	ds_write_b128 v222, v[128:131]
	s_and_b64 exec, s[70:71], s[40:41]
	ds_write_b128 v223, v[132:135]
	s_mov_b64 exec, -1
	s_add_i32 s0, s0, s1
	s_add_i32 s0, s0, 3
	s_lshr_b32 s0, s0, 2
	s_add_i32 s75, s75, s0
	v_cmp_eq_u32_e64 s[68:69], s74, v194
	v_cmp_eq_u32_e64 s[70:71], s74, v195
	s_nop 0
	s_lshl_b32 s3, s75, 2
	s_sub_i32 s3, s3, s37
	s_bcnt1_i32_b64 s0, s[68:69]
	s_bcnt1_i32_b64 s1, s[70:71]
	v_mbcnt_lo_u32_b32 v222, s68, 0
	v_mbcnt_hi_u32_b32 v222, s69, v222
	v_mbcnt_lo_u32_b32 v223, s70, 0
	v_mbcnt_hi_u32_b32 v223, s71, v223
	v_add_u32_e32 v222, s3, v222
	v_add_u32_e32 v223, s0, v223
	v_add_u32_e32 v223, s3, v223
	v_cmp_gt_u32_e64 s[38:39], s42, v222
	v_cmp_gt_u32_e64 s[40:41], s42, v223
	v_lshl_add_u32 v222, v222, 4, s22
	v_lshl_add_u32 v223, v223, 4, s22
	s_and_b64 exec, s[68:69], s[38:39]
	ds_write_b128 v222, v[136:139]
	s_and_b64 exec, s[70:71], s[40:41]
	ds_write_b128 v223, v[140:143]
	s_mov_b64 exec, -1
	s_add_i32 s0, s0, s1
	s_add_i32 s0, s0, 3
	s_lshr_b32 s0, s0, 2
	s_add_i32 s75, s75, s0
	v_cmp_eq_u32_e64 s[68:69], s74, v196
	v_cmp_eq_u32_e64 s[70:71], s74, v197
	s_nop 0
	s_lshl_b32 s3, s75, 2
	s_sub_i32 s3, s3, s37
	s_bcnt1_i32_b64 s0, s[68:69]
	s_bcnt1_i32_b64 s1, s[70:71]
	v_mbcnt_lo_u32_b32 v222, s68, 0
	v_mbcnt_hi_u32_b32 v222, s69, v222
	v_mbcnt_lo_u32_b32 v223, s70, 0
	v_mbcnt_hi_u32_b32 v223, s71, v223
	v_add_u32_e32 v222, s3, v222
	v_add_u32_e32 v223, s0, v223
	v_add_u32_e32 v223, s3, v223
	v_cmp_gt_u32_e64 s[38:39], s42, v222
	v_cmp_gt_u32_e64 s[40:41], s42, v223
	v_lshl_add_u32 v222, v222, 4, s22
	v_lshl_add_u32 v223, v223, 4, s22
	s_and_b64 exec, s[68:69], s[38:39]
	ds_write_b128 v222, v[144:147]
	s_and_b64 exec, s[70:71], s[40:41]
	ds_write_b128 v223, v[148:151]
	s_mov_b64 exec, -1
	s_add_i32 s0, s0, s1
; __device__ __forceinline__ void peer_tile(const Args& A, LAS unsigned char* lds, int tile) {
;     ...
;     for (int ti = 0; ti < 8; ++ti) {
;         const int tl = 8 * w + ti;
;         const u32x2 e0 = SEL[tl * 128 + lane], e1 = SEL[tl * 128 + 64 + lane];
;         const int p0 = (int)(e0.x >> 10), p1 = (int)(e1.x >> 10);
;         int off = 0;
;         for (int p = 0; p < 16; ++p) {
;             const unsigned long long m0 = __ballot(p0 == p), m1 = __ballot(p1 == p);
;             const int c0 = __popcll(m0), c1 = __popcll(m1);
;             const int r0 = __builtin_amdgcn_mbcnt_hi((unsigned)(m0 >> 32), __builtin_amdgcn_mbcnt_lo((unsigned)m0, 0u));
;             const int r1 = __builtin_amdgcn_mbcnt_hi((unsigned)(m1 >> 32), __builtin_amdgcn_mbcnt_lo((unsigned)m1, 0u));
;             if (p0 == p) SORT[tl * 128 + off + r0] = e0;
;             if (p1 == p) SORT[tl * 128 + off + c0 + r1] = e1;
;             if (lane == 0) OFFS[tl * 17 + p] = off;
;             off += c0 + c1;
;         }
;         if (lane == 0) OFFS[tl * 17 + 16] = off;
;     }
	s_add_i32 s0, s0, 3
	s_lshr_b32 s0, s0, 2
	s_add_i32 s75, s75, s0
	v_cmp_eq_u32_e64 s[68:69], s74, v198
	v_cmp_eq_u32_e64 s[70:71], s74, v199
	s_nop 0
	s_lshl_b32 s3, s75, 2
	s_sub_i32 s3, s3, s37
	s_bcnt1_i32_b64 s0, s[68:69]
	s_bcnt1_i32_b64 s1, s[70:71]
	v_mbcnt_lo_u32_b32 v222, s68, 0
	v_mbcnt_hi_u32_b32 v222, s69, v222
	v_mbcnt_lo_u32_b32 v223, s70, 0
	v_mbcnt_hi_u32_b32 v223, s71, v223
	v_add_u32_e32 v222, s3, v222
	v_add_u32_e32 v223, s0, v223
	v_add_u32_e32 v223, s3, v223
	v_cmp_gt_u32_e64 s[38:39], s42, v222
	v_cmp_gt_u32_e64 s[40:41], s42, v223
	v_lshl_add_u32 v222, v222, 4, s22
	v_lshl_add_u32 v223, v223, 4, s22
	s_and_b64 exec, s[68:69], s[38:39]
	ds_write_b128 v222, v[152:155]
	s_and_b64 exec, s[70:71], s[40:41]
	ds_write_b128 v223, v[156:159]
	s_mov_b64 exec, -1
	s_add_i32 s0, s0, s1
	s_add_i32 s0, s0, 3
	s_lshr_b32 s0, s0, 2
	s_add_i32 s75, s75, s0
	v_cmp_eq_u32_e64 s[68:69], s74, v200
	v_cmp_eq_u32_e64 s[70:71], s74, v201
	s_nop 0
	s_lshl_b32 s3, s75, 2
	s_sub_i32 s3, s3, s37
	s_bcnt1_i32_b64 s0, s[68:69]
	s_bcnt1_i32_b64 s1, s[70:71]
	v_mbcnt_lo_u32_b32 v222, s68, 0
	v_mbcnt_hi_u32_b32 v222, s69, v222
	v_mbcnt_lo_u32_b32 v223, s70, 0
	v_mbcnt_hi_u32_b32 v223, s71, v223
	v_add_u32_e32 v222, s3, v222
	v_add_u32_e32 v223, s0, v223
	v_add_u32_e32 v223, s3, v223
	v_cmp_gt_u32_e64 s[38:39], s42, v222
	v_cmp_gt_u32_e64 s[40:41], s42, v223
	v_lshl_add_u32 v222, v222, 4, s22
	v_lshl_add_u32 v223, v223, 4, s22
	s_and_b64 exec, s[68:69], s[38:39]
	ds_write_b128 v222, v[160:163]
	s_and_b64 exec, s[70:71], s[40:41]
	ds_write_b128 v223, v[164:167]
	s_mov_b64 exec, -1
	s_add_i32 s0, s0, s1
	s_add_i32 s0, s0, 3
	s_lshr_b32 s0, s0, 2
	s_add_i32 s75, s75, s0
	v_cmp_eq_u32_e64 s[68:69], s74, v202
	v_cmp_eq_u32_e64 s[70:71], s74, v203
	s_nop 0
	s_lshl_b32 s3, s75, 2
	s_sub_i32 s3, s3, s37
	s_bcnt1_i32_b64 s0, s[68:69]
	s_bcnt1_i32_b64 s1, s[70:71]
	v_mbcnt_lo_u32_b32 v222, s68, 0
	v_mbcnt_hi_u32_b32 v222, s69, v222
	v_mbcnt_lo_u32_b32 v223, s70, 0
	v_mbcnt_hi_u32_b32 v223, s71, v223
	v_add_u32_e32 v222, s3, v222
	v_add_u32_e32 v223, s0, v223
	v_add_u32_e32 v223, s3, v223
	v_cmp_gt_u32_e64 s[38:39], s42, v222
	v_cmp_gt_u32_e64 s[40:41], s42, v223
	v_lshl_add_u32 v222, v222, 4, s22
	v_lshl_add_u32 v223, v223, 4, s22
	s_and_b64 exec, s[68:69], s[38:39]
	ds_write_b128 v222, v[168:171]
	s_and_b64 exec, s[70:71], s[40:41]
	ds_write_b128 v223, v[172:175]
	s_mov_b64 exec, -1
	s_add_i32 s0, s0, s1
	s_add_i32 s0, s0, 3
	s_lshr_b32 s0, s0, 2
	s_add_i32 s75, s75, s0
	v_cmp_eq_u32_e64 s[68:69], s74, v204
	v_cmp_eq_u32_e64 s[70:71], s74, v205
	s_nop 0
	s_lshl_b32 s3, s75, 2
	s_sub_i32 s3, s3, s37
	s_bcnt1_i32_b64 s0, s[68:69]
	s_bcnt1_i32_b64 s1, s[70:71]
	v_mbcnt_lo_u32_b32 v222, s68, 0
	v_mbcnt_hi_u32_b32 v222, s69, v222
	v_mbcnt_lo_u32_b32 v223, s70, 0
	v_mbcnt_hi_u32_b32 v223, s71, v223
	v_add_u32_e32 v222, s3, v222
	v_add_u32_e32 v223, s0, v223
	v_add_u32_e32 v223, s3, v223
	v_cmp_gt_u32_e64 s[38:39], s42, v222
	v_cmp_gt_u32_e64 s[40:41], s42, v223
	v_lshl_add_u32 v222, v222, 4, s22
	v_lshl_add_u32 v223, v223, 4, s22
	s_and_b64 exec, s[68:69], s[38:39]
	ds_write_b128 v222, v[176:179]
	s_and_b64 exec, s[70:71], s[40:41]
	ds_write_b128 v223, v[180:183]
	s_mov_b64 exec, -1
	s_add_i32 s0, s0, s1
	s_add_i32 s0, s0, 3
	s_lshr_b32 s0, s0, 2
	s_add_i32 s75, s75, s0
	v_cmp_eq_u32_e64 s[68:69], s74, v206
	v_cmp_eq_u32_e64 s[70:71], s74, v207
	s_nop 0
	s_lshl_b32 s3, s75, 2
	s_sub_i32 s3, s3, s37
	s_bcnt1_i32_b64 s0, s[68:69]
	s_bcnt1_i32_b64 s1, s[70:71]
	v_mbcnt_lo_u32_b32 v222, s68, 0
	v_mbcnt_hi_u32_b32 v222, s69, v222
	v_mbcnt_lo_u32_b32 v223, s70, 0
	v_mbcnt_hi_u32_b32 v223, s71, v223
	v_add_u32_e32 v222, s3, v222
	v_add_u32_e32 v223, s0, v223
	v_add_u32_e32 v223, s3, v223
	v_cmp_gt_u32_e64 s[38:39], s42, v222
	v_cmp_gt_u32_e64 s[40:41], s42, v223
	v_lshl_add_u32 v222, v222, 4, s22
	v_lshl_add_u32 v223, v223, 4, s22
	s_and_b64 exec, s[68:69], s[38:39]
	ds_write_b128 v222, v[184:187]
	s_and_b64 exec, s[70:71], s[40:41]
	ds_write_b128 v223, v[188:191]
	s_mov_b64 exec, -1
	s_add_i32 s0, s0, s1
	s_add_i32 s0, s0, 3
	s_lshr_b32 s0, s0, 2
	s_add_i32 s75, s75, s0
	s_mov_b32 s91, s75
	s_sub_i32 s20, s91, s90
	s_min_u32 s20, s20, 128
	s_waitcnt vmcnt(0) lgkmcnt(0)
	v_add_u32_e32 v241, s22, v247
	ds_read_b128 v[232:235], v241 offset:0
	s_waitcnt lgkmcnt(0)
	v_readlane_b32 s64, v232, 0
	v_readlane_b32 s65, v232, 16
	v_readlane_b32 s66, v232, 32
	v_readlane_b32 s67, v232, 48
	s_add_u32 s24, s6, s64
	s_addc_u32 s25, s7, 0
	s_add_u32 s26, s6, s65
	s_addc_u32 s27, s7, 0
	s_add_u32 s28, s6, s66
	s_addc_u32 s29, s7, 0
	s_add_u32 s30, s6, s67
	s_addc_u32 s31, s7, 0
	global_load_dwordx4 v[128:131], v240, s[24:25]
	global_load_dwordx4 v[132:135], v240, s[26:27]
	global_load_dwordx4 v[136:139], v240, s[28:29]
	global_load_dwordx4 v[140:143], v240, s[30:31]
	ds_read_b128 v[232:235], v241 offset:64
	s_waitcnt lgkmcnt(0)
	v_readlane_b32 s64, v232, 0
	v_readlane_b32 s65, v232, 16
	v_readlane_b32 s66, v232, 32
	v_readlane_b32 s67, v232, 48
	s_add_u32 s24, s6, s64
	s_addc_u32 s25, s7, 0
	s_add_u32 s26, s6, s65
	s_addc_u32 s27, s7, 0
	s_add_u32 s28, s6, s66
	s_addc_u32 s29, s7, 0
	s_add_u32 s30, s6, s67
	s_addc_u32 s31, s7, 0
	global_load_dwordx4 v[144:147], v240, s[24:25]
	global_load_dwordx4 v[148:151], v240, s[26:27]
	global_load_dwordx4 v[152:155], v240, s[28:29]
	global_load_dwordx4 v[156:159], v240, s[30:31]
	ds_read_b128 v[232:235], v241 offset:128
	s_waitcnt lgkmcnt(0)
	v_readlane_b32 s64, v232, 0
	v_readlane_b32 s65, v232, 16
	v_readlane_b32 s66, v232, 32
	v_readlane_b32 s67, v232, 48
	s_add_u32 s24, s6, s64
	s_addc_u32 s25, s7, 0
	s_add_u32 s26, s6, s65
	s_addc_u32 s27, s7, 0
	s_add_u32 s28, s6, s66
	s_addc_u32 s29, s7, 0
	s_add_u32 s30, s6, s67
	s_addc_u32 s31, s7, 0
	global_load_dwordx4 v[160:163], v240, s[24:25]
	global_load_dwordx4 v[164:167], v240, s[26:27]
	global_load_dwordx4 v[168:171], v240, s[28:29]
	global_load_dwordx4 v[172:175], v240, s[30:31]
	ds_read_b128 v[232:235], v241 offset:192
	s_waitcnt lgkmcnt(0)
	v_readlane_b32 s64, v232, 0
	v_readlane_b32 s65, v232, 16
	v_readlane_b32 s66, v232, 32
	v_readlane_b32 s67, v232, 48
	s_add_u32 s24, s6, s64
	s_addc_u32 s25, s7, 0
	s_add_u32 s26, s6, s65
	s_addc_u32 s27, s7, 0
	s_add_u32 s28, s6, s66
	s_addc_u32 s29, s7, 0
	s_add_u32 s30, s6, s67
	s_addc_u32 s31, s7, 0
	global_load_dwordx4 v[176:179], v240, s[24:25]
	global_load_dwordx4 v[180:183], v240, s[26:27]
	global_load_dwordx4 v[184:187], v240, s[28:29]
	global_load_dwordx4 v[188:191], v240, s[30:31]
	ds_read_b128 v[236:239], v241 offset:0
	ds_read_b128 v[232:235], v241 offset:256
	s_mov_b32 s21, 0
